# W_out base prefetch moved to the last four K-iterations, two waves per iteration (closer to the epilogue: L2 rather than MALL hits)
# speedup vs baseline: 1.0003x; 1.0003x over previous
; #define SEAM(k) do { if ((k) + 1 < ph_hi) xcd_barrier(xbar); } while (0)
; template <class Epi, class Sched, bool ALIGN_EPI = false, bool SP2 = false>
; __device__ __forceinline__ void gemm_phase(PG8_LAS unsigned char* lds, const Gemm g, const Sched& S, const Epi& E) {
;     const int tid = threadIdx.x, wid = __builtin_amdgcn_readfirstlane(tid >> 6), lane = tid & 63, wr = wid >> 2, wc = wid & 3, fr = lane & 15, fq = lane >> 4;
;     const int K = g.K, nt = K / BK;
;     unsigned voffA[2], voffB[2];
; #pragma unroll
;     for (int i = 0; i < 2; ++i) { int R, C; stage_rc(tid * 16 + i * 8192, R, C); const int Rb = Epi::PERM ? ((R & ~31) + perm32(R & 31)) : R;
;         voffA[i] = (unsigned)(R * K + C) * 2u; voffB[i] = (unsigned)(Rb * K + C) * 2u; }
;     const size_t kstep = (size_t)(BK * 2);
;     const size_t hstep = (size_t)HALF * K * 2;
;     const size_t tstep = 2 * hstep;
;     const unsigned ldsw = (unsigned)wid * 1024u;
;     const int aoff = lds_byte(wr * 64 + fr, fq * 8), boff = lds_byte(wc * 32 + fr, fq * 8);
;     ...
;     Unit cur, nxt; int ui = 0;
;     if (!S.next(0, cur)) return;
; __global__ void __launch_bounds__(NTHREADS, 2) mega(Params P, int ph_lo, int ph_hi) {
;     ...
;     if (IN(10)) { pg8::Gemm g{(const bf16*)(ws + OFF_RA), (const bf16*)(ws + OFF_WOUT), MMAIN, DM, DM}; pg8::StaticOrder S; S.init(MMAIN, DM, G, (int)blockIdx.x);
;         pg8::EpiResid E{nullptr, (const bf16*)P.out, nullptr, nullptr, (bf16*)(ws + OFF_HB2), ss2, 1.0f}; pg8::gemm_phase<pg8::EpiResid, pg8::StaticOrder, true, true>(lds, g, S, E); SEAM(10); }
.LBB0_996:
	s_add_u32 s0, s86, 0x2b52400
	s_addc_u32 s1, s87, 0
	s_cmp_gt_i32 s88, 10
	s_cselect_b64 s[2:3], -1, 0
	s_cmp_lt_i32 s89, 11
	s_cselect_b64 s[4:5], -1, 0
	s_or_b64 s[2:3], s[2:3], s[4:5]
	s_and_b64 vcc, exec, s[2:3]
	s_cbranch_vccnz .LBB0_1093
	v_readfirstlane_b32 s101, v209
	v_lshrrev_b32_e32 v240, 1, v209
	v_and_b32_e32 v241, 1, v209
	v_lshlrev_b32_e32 v240, 11, v240
	v_lshl_add_u32 v240, v241, 8, v240
	s_lshr_b32 s101, s101, 7
	s_lshl_b32 s101, s101, 1
	s_add_i32 s101, s101, 6
	s_cmpk_lt_i32 s33, 0x100
	s_cselect_b64 s[2:3], -1, 0
	s_cmpk_gt_i32 s33, 0xff
	v_readfirstlane_b32 s12, v209
	s_cbranch_scc1 .LBB0_1000
	s_ashr_i32 s4, s33, 31
	s_lshr_b32 s4, s4, 29
	s_add_i32 s6, s33, s4
	s_and_b32 s4, s6, -8
	s_sub_i32 s7, s33, s4
	s_cmp_gt_i32 s7, -1
	s_cbranch_scc0 .LBB0_1036
	s_lshl_b32 s8, s7, 5
	s_cbranch_execz .LBB0_1037
	s_branch .LBB0_1038
